# early barrier invalidate also at the in-loop grid barrier after R5 (all 18 sites)
# baseline (speedup 1.0000x reference)
; __device__ __forceinline__ unsigned xb_ld(unsigned* p)              { return __hip_atomic_load(p, __ATOMIC_RELAXED, __HIP_MEMORY_SCOPE_AGENT); }
; __device__ __forceinline__ unsigned xb_add(unsigned* p, unsigned v) { return __hip_atomic_fetch_add(p, v, __ATOMIC_RELAXED, __HIP_MEMORY_SCOPE_AGENT); }
; #define XB_SPIN(cond, bar) do { unsigned _sp = 0; while (cond) { __builtin_amdgcn_s_sleep(1); \
;     if ((++_sp & 255u) == 0u) { if (xb_ld(&(bar)[XB_TMO])) break; if (_sp > XB_SPIN_CAP) { atomicAdd(&(bar)[XB_TMO], 1u); break; } } } } while (0)
; __device__ __forceinline__ void xcd_barrier(const XcdBarrier& b) {
;     asm volatile("s_waitcnt vmcnt(0)" ::: "memory");
;     __syncthreads();
;     if (threadIdx.x == 0) {
;         unsigned* bar = b.bar;
;         __builtin_amdgcn_s_waitcnt(0);
;         unsigned nloc = b.st[0], nx = b.st[1];
;         if (nloc == 0u) { xcd_barrier_complete(bar, b.x, nloc, nx); b.st[0] = nloc; b.st[1] = nx; }
;         const unsigned old = xb_add(&bar[XB_XSUB(b.x)], 1u);
;         const unsigned gen = old / nloc;
;         if (old + 1u == (gen + 1u) * nloc) {
;             __builtin_amdgcn_fence(__ATOMIC_RELEASE, "agent");
;             asm volatile("s_waitcnt vmcnt(0)" ::: "memory");
;             const unsigned og = xb_add(&bar[XB_TOP], 1u);
;             const unsigned tg = og / nx;
;             if (og + 1u == (tg + 1u) * nx) xb_add(&bar[XB_TOPGEN], 1u);
;             else XB_SPIN(xb_ld(&bar[XB_TOPGEN]) == tg, bar);
;             __builtin_amdgcn_fence(__ATOMIC_ACQUIRE, "agent");
;             xb_add(&bar[XB_XGEN(b.x)], 1u);
;             asm volatile("s_waitcnt vmcnt(0)" ::: "memory");
;         } else {
;             XB_SPIN(xb_ld(&bar[XB_XGEN(b.x)]) == gen, bar);
;             __builtin_amdgcn_fence(__ATOMIC_ACQUIRE, "agent");
;             asm volatile("s_waitcnt vmcnt(0)" ::: "memory");
;         }
;     }
;     __syncthreads();
; }
.LBB0_905:
	s_or_b64 exec, exec, s[8:9]
	s_mov_b64 s[8:9], exec
	v_mbcnt_lo_u32_b32 v0, s8, 0
	v_mbcnt_hi_u32_b32 v0, s9, v0
	v_cmp_eq_u32_e32 vcc, 0, v0
	s_waitcnt vmcnt(0)
	s_and_saveexec_b64 s[16:17], vcc
	s_cbranch_execz .LBB0_475
	s_bcnt1_i32_b64 s4, s[8:9]
	v_mov_b32_e32 v0, s4
	v_mov_b32_e32 v1, 0x2000
	global_atomic_add v1, v0, s[10:11] offset:1024
	s_branch .LBB0_475
.Lgsinv_r5:
	s_mov_b64 exec, s[6:7]
	v_readfirstlane_b32 s10, v176
	s_cmp_lg_u32 s10, 64
	s_cbranch_scc1 .LBB0_476
	buffer_inv sc1
	s_waitcnt vmcnt(0)
	s_branch .LBB0_476
